# sample_ssd item: wave reductions via DPP/permlane swaps instead of ds_bpermute; z, dt, A_log loads and pointer fetches issued at item start instead of one after another
# baseline (speedup 1.0000x reference)
.LBB0_323:
	s_and_b64 vcc, exec, s[4:5]
	s_cbranch_vccz .LBB0_398
	v_mov_b32_e32 v6, v201
	s_movk_i32 s2, 0x400
	s_add_i32 s6, s24, 0x7f80
	s_mov_b32 s7, s3
	v_readlane_b32 s98, v253, 42
	v_readlane_b32 s99, v253, 43
	s_nop 0
	s_load_dwordx2 s[100:101], s[98:99], 0x90
	s_load_dwordx2 s[98:99], s[98:99], 0x30
	s_mul_i32 s8, s6, 0x1400
	s_mul_hi_u32 s9, s6, 0x1400
	v_readlane_b32 s10, v254, 1
	v_readlane_b32 s11, v254, 2
	s_add_u32 s8, s10, s8
	s_addc_u32 s9, s11, s9
	v_ashrrev_i32_e32 v91, 31, v6
	v_mov_b32_e32 v90, v6
	v_lshl_add_u64 v[90:91], v[90:91], 1, s[8:9]
	global_load_ushort v94, v[90:91], off offset:2048
	s_lshl_b64 s[8:9], s[6:7], 5
	v_readlane_b32 s10, v254, 11
	v_readlane_b32 s11, v254, 12
	s_add_u32 s8, s10, s8
	s_addc_u32 s9, s11, s9
	v_ashrrev_i32_e32 v90, 6, v6
	v_ashrrev_i32_e32 v91, 31, v90
	v_lshl_add_u64 v[92:93], v[90:91], 2, s[8:9]
	global_load_dword v81, v[92:93], off
	v_readlane_b32 s8, v253, 58
	v_add_u32_e32 v90, s8, v90
	v_ashrrev_i32_e32 v91, 31, v90
	s_waitcnt lgkmcnt(0)
	v_lshl_add_u64 v[92:93], v[90:91], 2, s[100:101]
	global_load_dword v95, v[92:93], off
	v_cmp_gt_i32_e32 vcc, s2, v6
	s_barrier
	s_and_saveexec_b64 s[4:5], vcc
	s_movk_i32 s2, 0x1ff
	s_cbranch_execz .LBB0_332
	v_max_i32_e32 v0, 0x200, v6
	v_sub_u32_e32 v0, v0, v6
	v_add_u32_e32 v0, 0x1ff, v0
	v_cmp_lt_u32_e32 vcc, s2, v0
	s_mov_b64 s[10:11], -1
	v_mov_b32_e32 v2, v6
	s_and_saveexec_b64 s[8:9], vcc
	s_cbranch_execz .LBB0_329
	v_lshrrev_b32_e32 v0, 9, v0
	s_lshl_b64 s[10:11], s[6:7], 11
	v_readlane_b32 s20, v253, 46
	v_add_u32_e32 v0, 1, v0
	v_readlane_b32 s21, v253, 47
	s_add_u32 s10, s20, s10
	v_and_b32_e32 v4, 0xfffffe, v0
	v_add_u32_e32 v7, 0x200, v6
	s_addc_u32 s11, s21, s11
	v_lshl_add_u32 v5, v6, 2, 0
	s_mov_b64 s[18:19], 0
	v_mov_b32_e32 v8, v4
	v_mov_b64_e32 v[2:3], v[6:7]
	v_readlane_b32 s22, v253, 48
	v_readlane_b32 s23, v253, 49

.LBB0_332:
	s_or_b64 exec, exec, s[4:5]
	s_add_i32 s2, s24, 0xffffff80
	v_readlane_b32 s4, v254, 18
	s_add_i32 s4, s2, s4
	s_mul_i32 s5, s6, 0x1400
	v_readlane_b32 s8, v254, 1
	s_mul_hi_u32 s2, s6, 0x1400
	v_readlane_b32 s9, v254, 2
	s_add_u32 s8, s8, s5
	v_ashrrev_i32_e32 v7, 31, v6
	s_addc_u32 s9, s9, s2
	v_lshl_add_u64 v[2:3], v[6:7], 1, s[8:9]
	s_lshl_b64 s[8:9], s[6:7], 5
	v_readlane_b32 s10, v254, 11
	v_readlane_b32 s11, v254, 12
	s_add_u32 s8, s10, s8
	v_ashrrev_i32_e32 v8, 6, v6
	s_addc_u32 s9, s11, s9
	v_readlane_b32 s10, v253, 42
	v_lshl_add_u32 v80, v6, 2, 0
	v_ashrrev_i32_e32 v9, 31, v8
	v_readlane_b32 s11, v253, 43
	v_lshl_add_u64 v[2:3], v[8:9], 2, s[8:9]
	v_readlane_b32 s2, v253, 58
	s_ashr_i32 s5, s4, 31
	v_lshlrev_b64 v[14:15], 13, v[8:9]
	v_add_u32_e32 v10, s2, v8
	v_ashrrev_i32_e32 v11, 31, v10
	s_lshl_b64 s[4:5], s[4:5], 16
	v_lshl_add_u64 v[14:15], v[14:15], 0, s[4:5]
	v_and_b32_e32 v13, 63, v6
	v_lshlrev_b64 v[14:15], 2, v[14:15]
	v_lshl_add_u64 v[18:19], s[12:13], 0, v[14:15]
	v_and_b32_e32 v9, 0xffffffc0, v6
	s_mov_b32 s17, 0
	v_cmp_eq_u32_e64 s[4:5], 0, v13
	s_waitcnt vmcnt(0)
	v_lshlrev_b32_e32 v0, 16, v94
	ds_write_b32 v80, v0 offset:4096
	s_waitcnt lgkmcnt(0)
	s_barrier
	s_mov_b64 s[8:9], s[98:99]
	v_lshl_add_u64 v[16:17], s[8:9], 0, v[14:15]
	s_mov_b64 s[8:9], -1
	s_waitcnt vmcnt(0)
	v_mul_f32_e32 v0, 0x3fb8aa3b, v95
	v_exp_f32_e32 v0, v0
	s_nop 0
	v_mul_f32_e64 v0, v81, -v0
	v_mul_f32_e32 v0, 0x3fb8aa3b, v0
	v_exp_f32_e32 v12, v0
	v_lshlrev_b32_e32 v0, 1, v6
	v_and_b32_e32 v2, 0xfffffe00, v0
	v_lshlrev_b32_e32 v0, 3, v13
	v_add3_u32 v2, 0, v2, v0
	v_lshl_add_u64 v[14:15], v[16:17], 0, v[0:1]
	v_lshl_add_u64 v[16:17], v[18:19], 0, v[0:1]
	v_and_b32_e32 v0, 64, v243
	v_add_u32_e32 v18, 64, v0
	v_xor_b32_e32 v0, 32, v243
	v_cmp_lt_i32_e32 vcc, v0, v18
	v_xor_b32_e32 v19, 16, v243
	ds_read2st64_b64 v[2:5], v2 offset0:4 offset1:6
	v_cndmask_b32_e32 v0, v243, v0, vcc
	v_cmp_lt_i32_e32 vcc, v19, v18
	v_lshlrev_b32_e32 v0, 2, v0
	v_mov_b32_e32 v13, v12
	v_cndmask_b32_e32 v19, v243, v19, vcc
	v_lshlrev_b32_e32 v82, 2, v19
	v_xor_b32_e32 v19, 8, v243
	v_cmp_lt_i32_e32 vcc, v19, v18
	s_nop 1
	v_cndmask_b32_e32 v19, v243, v19, vcc
	v_lshlrev_b32_e32 v83, 2, v19
	v_xor_b32_e32 v19, 4, v243
	v_cmp_lt_i32_e32 vcc, v19, v18
	s_nop 1
	v_cndmask_b32_e32 v19, v243, v19, vcc
	v_lshlrev_b32_e32 v84, 2, v19
	v_xor_b32_e32 v19, 2, v243
	v_cmp_lt_i32_e32 vcc, v19, v18
	s_nop 1
	v_cndmask_b32_e32 v19, v243, v19, vcc
	v_lshlrev_b32_e32 v85, 2, v19
	v_xor_b32_e32 v19, 1, v243
	v_cmp_lt_i32_e32 vcc, v19, v18
	s_nop 1
	v_cndmask_b32_e32 v18, v243, v19, vcc
	v_lshlrev_b32_e32 v86, 2, v18
	s_branch .LBB0_334
	s_nop 0
	s_nop 0
	s_nop 0
	s_nop 0
	s_nop 0
	s_nop 0
	s_nop 0
	s_nop 0
	s_nop 0
	s_nop 0
	s_nop 0
	s_nop 0
	s_nop 0
	s_nop 0
	s_nop 0

.LBB0_334:
	s_lshl_b32 s2, s17, 7
	s_lshl_b64 s[10:11], s[2:3], 2
	s_waitcnt lgkmcnt(0)
	v_lshl_add_u64 v[18:19], v[14:15], 0, s[10:11]
	global_load_dwordx2 v[72:73], v[18:19], off offset:2048
	global_load_dwordx2 v[70:71], v[18:19], off offset:2560
	global_load_dwordx2 v[68:69], v[18:19], off offset:3072
	global_load_dwordx2 v[64:65], v[18:19], off offset:3584
	global_load_dwordx2 v[78:79], v[18:19], off offset:512
	global_load_dwordx2 v[76:77], v[18:19], off offset:1024
	global_load_dwordx2 v[74:75], v[18:19], off offset:1536
	global_load_dwordx2 v[88:89], v[18:19], off
	v_add_co_u32_e32 v20, vcc, 0x1000, v18
	s_movk_i32 s18, 0x2000
	s_nop 0
	v_addc_co_u32_e32 v21, vcc, 0, v19, vcc
	global_load_dwordx2 v[66:67], v[20:21], off
	global_load_dwordx2 v[62:63], v[20:21], off offset:512
	global_load_dwordx2 v[60:61], v[20:21], off offset:1024
	global_load_dwordx2 v[58:59], v[20:21], off offset:1536
	global_load_dwordx2 v[56:57], v[20:21], off offset:2048
	global_load_dwordx2 v[54:55], v[20:21], off offset:2560
	global_load_dwordx2 v[52:53], v[20:21], off offset:3072
	global_load_dwordx2 v[50:51], v[20:21], off offset:3584
	v_add_co_u32_e32 v20, vcc, s18, v18
	s_movk_i32 s18, 0x3000
	s_nop 0
	v_addc_co_u32_e32 v21, vcc, 0, v19, vcc
	v_add_co_u32_e32 v18, vcc, s18, v18
	v_or_b32_e32 v87, s17, v9
	s_nop 0
	v_addc_co_u32_e32 v19, vcc, 0, v19, vcc
	global_load_dwordx2 v[46:47], v[20:21], off offset:512
	global_load_dwordx2 v[44:45], v[20:21], off offset:1024
	global_load_dwordx2 v[42:43], v[20:21], off offset:1536
	global_load_dwordx2 v[40:41], v[20:21], off offset:2048
	global_load_dwordx2 v[48:49], v[18:19], off offset:-4096
	global_load_dwordx2 v[38:39], v[20:21], off offset:2560
	global_load_dwordx2 v[36:37], v[20:21], off offset:3072
	global_load_dwordx2 v[34:35], v[20:21], off offset:3584
	global_load_dwordx2 v[32:33], v[18:19], off
	global_load_dwordx2 v[30:31], v[18:19], off offset:512
	global_load_dwordx2 v[28:29], v[18:19], off offset:1024
	global_load_dwordx2 v[26:27], v[18:19], off offset:1536
	global_load_dwordx2 v[24:25], v[18:19], off offset:2048
	global_load_dwordx2 v[22:23], v[18:19], off offset:2560
	global_load_dwordx2 v[20:21], v[18:19], off offset:3072
	s_nop 0
	global_load_dwordx2 v[18:19], v[18:19], off offset:3584
	v_lshl_add_u32 v87, v87, 2, 0
	s_waitcnt vmcnt(0)
	ds_read_b32 v96, v87
	ds_read_b32 v97, v87 offset:4
	ds_read_b32 v98, v87 offset:8
	ds_read_b32 v99, v87 offset:12
	ds_read_b32 v100, v87 offset:16
	ds_read_b32 v101, v87 offset:20
	ds_read_b32 v102, v87 offset:24
	ds_read_b32 v103, v87 offset:28
	ds_read_b32 v104, v87 offset:32
	ds_read_b32 v105, v87 offset:36
	ds_read_b32 v106, v87 offset:40
	ds_read_b32 v107, v87 offset:44
	ds_read_b32 v108, v87 offset:48
	ds_read_b32 v109, v87 offset:52
	ds_read_b32 v110, v87 offset:56
	ds_read_b32 v111, v87 offset:60
	s_waitcnt lgkmcnt(0)
	ds_read_b32 v112, v87 offset:64
	ds_read_b32 v113, v87 offset:68
	ds_read_b32 v114, v87 offset:72
	ds_read_b32 v115, v87 offset:76
	ds_read_b32 v116, v87 offset:80
	ds_read_b32 v117, v87 offset:84
	ds_read_b32 v118, v87 offset:88
	ds_read_b32 v119, v87 offset:92
	ds_read_b32 v120, v87 offset:96
	ds_read_b32 v121, v87 offset:100
	ds_read_b32 v122, v87 offset:104
	ds_read_b32 v123, v87 offset:108
	ds_read_b32 v124, v87 offset:112
	ds_read_b32 v125, v87 offset:116
	ds_read_b32 v126, v87 offset:120
	ds_read_b32 v127, v87 offset:124
	s_waitcnt lgkmcnt(0)
	v_mul_f32_e32 v128, v81, v96
	s_lshl_b64 s[10:11], s[2:3], 2
	v_lshl_add_u64 v[92:93], v[16:17], 0, s[10:11]
	v_pk_mul_f32 v[128:129], v[2:3], v[128:129] op_sel_hi:[1,0]
	s_nop 0
	v_pk_fma_f32 v[128:129], v[12:13], v[88:89], v[128:129]
	global_store_dwordx2 v[92:93], v[128:129], off
	v_mul_f32_e32 v96, v5, v129
	v_fmac_f32_e32 v96, v4, v128
	v_mul_f32_e32 v130, v81, v97
	s_or_b32 s10, s2, 0x80
	s_mov_b32 s11, s3
	v_lshl_add_u64 v[92:93], s[10:11], 2, v[16:17]
	v_pk_mul_f32 v[130:131], v[2:3], v[130:131] op_sel_hi:[1,0]
	s_nop 0
	v_pk_fma_f32 v[130:131], v[12:13], v[78:79], v[130:131]
	global_store_dwordx2 v[92:93], v[130:131], off
	v_mul_f32_e32 v97, v5, v131
	v_fmac_f32_e32 v97, v4, v130
	v_mul_f32_e32 v132, v81, v98
	s_or_b32 s10, s2, 0x100
	s_mov_b32 s11, s3
	v_lshl_add_u64 v[92:93], s[10:11], 2, v[16:17]
	v_pk_mul_f32 v[132:133], v[2:3], v[132:133] op_sel_hi:[1,0]
	s_nop 0
	v_pk_fma_f32 v[132:133], v[12:13], v[76:77], v[132:133]
	global_store_dwordx2 v[92:93], v[132:133], off
	v_mul_f32_e32 v98, v5, v133
	v_fmac_f32_e32 v98, v4, v132
	v_mul_f32_e32 v134, v81, v99
	s_or_b32 s10, s2, 0x180
	s_mov_b32 s11, s3
	v_lshl_add_u64 v[92:93], s[10:11], 2, v[16:17]
	v_pk_mul_f32 v[134:135], v[2:3], v[134:135] op_sel_hi:[1,0]
	s_nop 0
	v_pk_fma_f32 v[134:135], v[12:13], v[74:75], v[134:135]
	global_store_dwordx2 v[92:93], v[134:135], off
	v_mul_f32_e32 v99, v5, v135
	v_fmac_f32_e32 v99, v4, v134
	v_mul_f32_e32 v136, v81, v100
	s_or_b32 s10, s2, 0x200
	s_mov_b32 s11, s3
	v_lshl_add_u64 v[92:93], s[10:11], 2, v[16:17]
	v_pk_mul_f32 v[136:137], v[2:3], v[136:137] op_sel_hi:[1,0]
	s_nop 0
	v_pk_fma_f32 v[136:137], v[12:13], v[72:73], v[136:137]
	global_store_dwordx2 v[92:93], v[136:137], off
	v_mul_f32_e32 v100, v5, v137
	v_fmac_f32_e32 v100, v4, v136
	v_mul_f32_e32 v138, v81, v101
	s_or_b32 s10, s2, 0x280
	s_mov_b32 s11, s3
	v_lshl_add_u64 v[92:93], s[10:11], 2, v[16:17]
	v_pk_mul_f32 v[138:139], v[2:3], v[138:139] op_sel_hi:[1,0]
	s_nop 0
	v_pk_fma_f32 v[138:139], v[12:13], v[70:71], v[138:139]
	global_store_dwordx2 v[92:93], v[138:139], off
	v_mul_f32_e32 v101, v5, v139
	v_fmac_f32_e32 v101, v4, v138
	v_mul_f32_e32 v140, v81, v102
	s_or_b32 s10, s2, 0x300
	s_mov_b32 s11, s3
	v_lshl_add_u64 v[92:93], s[10:11], 2, v[16:17]
	v_pk_mul_f32 v[140:141], v[2:3], v[140:141] op_sel_hi:[1,0]
	s_nop 0
	v_pk_fma_f32 v[140:141], v[12:13], v[68:69], v[140:141]
	global_store_dwordx2 v[92:93], v[140:141], off
	v_mul_f32_e32 v102, v5, v141
	v_fmac_f32_e32 v102, v4, v140
	v_mul_f32_e32 v142, v81, v103
	s_or_b32 s10, s2, 0x380
	s_mov_b32 s11, s3
	v_lshl_add_u64 v[92:93], s[10:11], 2, v[16:17]
	v_pk_mul_f32 v[142:143], v[2:3], v[142:143] op_sel_hi:[1,0]
	s_nop 0
	v_pk_fma_f32 v[142:143], v[12:13], v[64:65], v[142:143]
	global_store_dwordx2 v[92:93], v[142:143], off
	v_mul_f32_e32 v103, v5, v143
	v_fmac_f32_e32 v103, v4, v142
	v_mul_f32_e32 v144, v81, v104
	s_or_b32 s10, s2, 0x400
	s_mov_b32 s11, s3
	v_lshl_add_u64 v[92:93], s[10:11], 2, v[16:17]
	v_pk_mul_f32 v[144:145], v[2:3], v[144:145] op_sel_hi:[1,0]
	s_nop 0
	v_pk_fma_f32 v[144:145], v[12:13], v[66:67], v[144:145]
	global_store_dwordx2 v[92:93], v[144:145], off
	v_mul_f32_e32 v104, v5, v145
	v_fmac_f32_e32 v104, v4, v144
	v_mul_f32_e32 v146, v81, v105
	s_or_b32 s10, s2, 0x480
	s_mov_b32 s11, s3
	v_lshl_add_u64 v[92:93], s[10:11], 2, v[16:17]
	v_pk_mul_f32 v[146:147], v[2:3], v[146:147] op_sel_hi:[1,0]
	s_nop 0
	v_pk_fma_f32 v[146:147], v[12:13], v[62:63], v[146:147]
	global_store_dwordx2 v[92:93], v[146:147], off
	v_mul_f32_e32 v105, v5, v147
	v_fmac_f32_e32 v105, v4, v146
	v_mul_f32_e32 v148, v81, v106
	s_or_b32 s10, s2, 0x500
	s_mov_b32 s11, s3
	v_lshl_add_u64 v[92:93], s[10:11], 2, v[16:17]
	v_pk_mul_f32 v[148:149], v[2:3], v[148:149] op_sel_hi:[1,0]
	s_nop 0
	v_pk_fma_f32 v[148:149], v[12:13], v[60:61], v[148:149]
	global_store_dwordx2 v[92:93], v[148:149], off
	v_mul_f32_e32 v106, v5, v149
	v_fmac_f32_e32 v106, v4, v148
	v_mul_f32_e32 v150, v81, v107
	s_or_b32 s10, s2, 0x580
	s_mov_b32 s11, s3
	v_lshl_add_u64 v[92:93], s[10:11], 2, v[16:17]
	v_pk_mul_f32 v[150:151], v[2:3], v[150:151] op_sel_hi:[1,0]
	s_nop 0
	v_pk_fma_f32 v[150:151], v[12:13], v[58:59], v[150:151]
	global_store_dwordx2 v[92:93], v[150:151], off
	v_mul_f32_e32 v107, v5, v151
	v_fmac_f32_e32 v107, v4, v150
	v_mul_f32_e32 v152, v81, v108
	s_or_b32 s10, s2, 0x600
	s_mov_b32 s11, s3
	v_lshl_add_u64 v[92:93], s[10:11], 2, v[16:17]
	v_pk_mul_f32 v[152:153], v[2:3], v[152:153] op_sel_hi:[1,0]
	s_nop 0
	v_pk_fma_f32 v[152:153], v[12:13], v[56:57], v[152:153]
	global_store_dwordx2 v[92:93], v[152:153], off
	v_mul_f32_e32 v108, v5, v153
	v_fmac_f32_e32 v108, v4, v152
	v_mul_f32_e32 v154, v81, v109
	s_or_b32 s10, s2, 0x680
	s_mov_b32 s11, s3
	v_lshl_add_u64 v[92:93], s[10:11], 2, v[16:17]
	v_pk_mul_f32 v[154:155], v[2:3], v[154:155] op_sel_hi:[1,0]
	s_nop 0
	v_pk_fma_f32 v[154:155], v[12:13], v[54:55], v[154:155]
	global_store_dwordx2 v[92:93], v[154:155], off
	v_mul_f32_e32 v109, v5, v155
	v_fmac_f32_e32 v109, v4, v154
	v_mul_f32_e32 v156, v81, v110
	s_or_b32 s10, s2, 0x700
	s_mov_b32 s11, s3
	v_lshl_add_u64 v[92:93], s[10:11], 2, v[16:17]
	v_pk_mul_f32 v[156:157], v[2:3], v[156:157] op_sel_hi:[1,0]
	s_nop 0
	v_pk_fma_f32 v[156:157], v[12:13], v[52:53], v[156:157]
	global_store_dwordx2 v[92:93], v[156:157], off
	v_mul_f32_e32 v110, v5, v157
	v_fmac_f32_e32 v110, v4, v156
	v_mul_f32_e32 v158, v81, v111
	s_or_b32 s10, s2, 0x780
	s_mov_b32 s11, s3
	v_lshl_add_u64 v[92:93], s[10:11], 2, v[16:17]
	v_pk_mul_f32 v[158:159], v[2:3], v[158:159] op_sel_hi:[1,0]
	s_nop 0
	v_pk_fma_f32 v[158:159], v[12:13], v[50:51], v[158:159]
	global_store_dwordx2 v[92:93], v[158:159], off
	v_mul_f32_e32 v111, v5, v159
	v_fmac_f32_e32 v111, v4, v158
	v_mul_f32_e32 v160, v81, v112
	s_or_b32 s10, s2, 0x800
	s_mov_b32 s11, s3
	v_lshl_add_u64 v[92:93], s[10:11], 2, v[16:17]
	v_pk_mul_f32 v[160:161], v[2:3], v[160:161] op_sel_hi:[1,0]
	s_nop 0
	v_pk_fma_f32 v[160:161], v[12:13], v[48:49], v[160:161]
	global_store_dwordx2 v[92:93], v[160:161], off
	v_mul_f32_e32 v112, v5, v161
	v_fmac_f32_e32 v112, v4, v160
	v_mul_f32_e32 v162, v81, v113
	s_or_b32 s10, s2, 0x880
	s_mov_b32 s11, s3
	v_lshl_add_u64 v[92:93], s[10:11], 2, v[16:17]
	v_pk_mul_f32 v[162:163], v[2:3], v[162:163] op_sel_hi:[1,0]
	s_nop 0
	v_pk_fma_f32 v[162:163], v[12:13], v[46:47], v[162:163]
	global_store_dwordx2 v[92:93], v[162:163], off
	v_mul_f32_e32 v113, v5, v163
	v_fmac_f32_e32 v113, v4, v162
	v_mul_f32_e32 v164, v81, v114
	s_or_b32 s10, s2, 0x900
	s_mov_b32 s11, s3
	v_lshl_add_u64 v[92:93], s[10:11], 2, v[16:17]
	v_pk_mul_f32 v[164:165], v[2:3], v[164:165] op_sel_hi:[1,0]
	s_nop 0
	v_pk_fma_f32 v[164:165], v[12:13], v[44:45], v[164:165]
	global_store_dwordx2 v[92:93], v[164:165], off
	v_mul_f32_e32 v114, v5, v165
	v_fmac_f32_e32 v114, v4, v164
	v_mul_f32_e32 v166, v81, v115
	s_or_b32 s10, s2, 0x980
	s_mov_b32 s11, s3
	v_lshl_add_u64 v[92:93], s[10:11], 2, v[16:17]
	v_pk_mul_f32 v[166:167], v[2:3], v[166:167] op_sel_hi:[1,0]
	s_nop 0
	v_pk_fma_f32 v[166:167], v[12:13], v[42:43], v[166:167]
	global_store_dwordx2 v[92:93], v[166:167], off
	v_mul_f32_e32 v115, v5, v167
	v_fmac_f32_e32 v115, v4, v166
	v_mul_f32_e32 v168, v81, v116
	s_or_b32 s10, s2, 0xa00
	s_mov_b32 s11, s3
	v_lshl_add_u64 v[92:93], s[10:11], 2, v[16:17]
	v_pk_mul_f32 v[168:169], v[2:3], v[168:169] op_sel_hi:[1,0]
	s_nop 0
	v_pk_fma_f32 v[168:169], v[12:13], v[40:41], v[168:169]
	global_store_dwordx2 v[92:93], v[168:169], off
	v_mul_f32_e32 v116, v5, v169
	v_fmac_f32_e32 v116, v4, v168
	v_mul_f32_e32 v170, v81, v117
	s_or_b32 s10, s2, 0xa80
	s_mov_b32 s11, s3
	v_lshl_add_u64 v[92:93], s[10:11], 2, v[16:17]
	v_pk_mul_f32 v[170:171], v[2:3], v[170:171] op_sel_hi:[1,0]
	s_nop 0
	v_pk_fma_f32 v[170:171], v[12:13], v[38:39], v[170:171]
	global_store_dwordx2 v[92:93], v[170:171], off
	v_mul_f32_e32 v117, v5, v171
	v_fmac_f32_e32 v117, v4, v170
	v_mul_f32_e32 v172, v81, v118
	s_or_b32 s10, s2, 0xb00
	s_mov_b32 s11, s3
	v_lshl_add_u64 v[92:93], s[10:11], 2, v[16:17]
	v_pk_mul_f32 v[172:173], v[2:3], v[172:173] op_sel_hi:[1,0]
	s_nop 0
	v_pk_fma_f32 v[172:173], v[12:13], v[36:37], v[172:173]
	global_store_dwordx2 v[92:93], v[172:173], off
	v_mul_f32_e32 v118, v5, v173
	v_fmac_f32_e32 v118, v4, v172
	v_mul_f32_e32 v174, v81, v119
	s_or_b32 s10, s2, 0xb80
	s_mov_b32 s11, s3
	v_lshl_add_u64 v[92:93], s[10:11], 2, v[16:17]
	v_pk_mul_f32 v[174:175], v[2:3], v[174:175] op_sel_hi:[1,0]
	s_nop 0
	v_pk_fma_f32 v[174:175], v[12:13], v[34:35], v[174:175]
	global_store_dwordx2 v[92:93], v[174:175], off
	v_mul_f32_e32 v119, v5, v175
	v_fmac_f32_e32 v119, v4, v174
	v_mul_f32_e32 v176, v81, v120
	s_or_b32 s10, s2, 0xc00
	s_mov_b32 s11, s3
	v_lshl_add_u64 v[92:93], s[10:11], 2, v[16:17]
	v_pk_mul_f32 v[176:177], v[2:3], v[176:177] op_sel_hi:[1,0]
	s_nop 0
	v_pk_fma_f32 v[176:177], v[12:13], v[32:33], v[176:177]
	global_store_dwordx2 v[92:93], v[176:177], off
	v_mul_f32_e32 v120, v5, v177
	v_fmac_f32_e32 v120, v4, v176
	v_mul_f32_e32 v178, v81, v121
	s_or_b32 s10, s2, 0xc80
	s_mov_b32 s11, s3
	v_lshl_add_u64 v[92:93], s[10:11], 2, v[16:17]
	v_pk_mul_f32 v[178:179], v[2:3], v[178:179] op_sel_hi:[1,0]
	s_nop 0
	v_pk_fma_f32 v[178:179], v[12:13], v[30:31], v[178:179]
	global_store_dwordx2 v[92:93], v[178:179], off
	v_mul_f32_e32 v121, v5, v179
	v_fmac_f32_e32 v121, v4, v178
	v_mul_f32_e32 v180, v81, v122
	s_or_b32 s10, s2, 0xd00
	s_mov_b32 s11, s3
	v_lshl_add_u64 v[92:93], s[10:11], 2, v[16:17]
	v_pk_mul_f32 v[180:181], v[2:3], v[180:181] op_sel_hi:[1,0]
	s_nop 0
	v_pk_fma_f32 v[180:181], v[12:13], v[28:29], v[180:181]
	global_store_dwordx2 v[92:93], v[180:181], off
	v_mul_f32_e32 v122, v5, v181
	v_fmac_f32_e32 v122, v4, v180
	v_mul_f32_e32 v182, v81, v123
	s_or_b32 s10, s2, 0xd80
	s_mov_b32 s11, s3
	v_lshl_add_u64 v[92:93], s[10:11], 2, v[16:17]
	v_pk_mul_f32 v[182:183], v[2:3], v[182:183] op_sel_hi:[1,0]
	s_nop 0
	v_pk_fma_f32 v[182:183], v[12:13], v[26:27], v[182:183]
	global_store_dwordx2 v[92:93], v[182:183], off
	v_mul_f32_e32 v123, v5, v183
	v_fmac_f32_e32 v123, v4, v182
	v_mul_f32_e32 v184, v81, v124
	s_or_b32 s10, s2, 0xe00
	s_mov_b32 s11, s3
	v_lshl_add_u64 v[92:93], s[10:11], 2, v[16:17]
	v_pk_mul_f32 v[184:185], v[2:3], v[184:185] op_sel_hi:[1,0]
	s_nop 0
	v_pk_fma_f32 v[184:185], v[12:13], v[24:25], v[184:185]
	global_store_dwordx2 v[92:93], v[184:185], off
	v_mul_f32_e32 v124, v5, v185
	v_fmac_f32_e32 v124, v4, v184
	v_mul_f32_e32 v186, v81, v125
	s_or_b32 s10, s2, 0xe80
	s_mov_b32 s11, s3
	v_lshl_add_u64 v[92:93], s[10:11], 2, v[16:17]
	v_pk_mul_f32 v[186:187], v[2:3], v[186:187] op_sel_hi:[1,0]
	s_nop 0
	v_pk_fma_f32 v[186:187], v[12:13], v[22:23], v[186:187]
	global_store_dwordx2 v[92:93], v[186:187], off
	v_mul_f32_e32 v125, v5, v187
	v_fmac_f32_e32 v125, v4, v186
	v_mul_f32_e32 v188, v81, v126
	s_or_b32 s10, s2, 0xf00
	s_mov_b32 s11, s3
	v_lshl_add_u64 v[92:93], s[10:11], 2, v[16:17]
	v_pk_mul_f32 v[188:189], v[2:3], v[188:189] op_sel_hi:[1,0]
	s_nop 0
	v_pk_fma_f32 v[188:189], v[12:13], v[20:21], v[188:189]
	global_store_dwordx2 v[92:93], v[188:189], off
	v_mul_f32_e32 v126, v5, v189
	v_fmac_f32_e32 v126, v4, v188
	v_mul_f32_e32 v190, v81, v127
	s_or_b32 s10, s2, 0xf80
	s_mov_b32 s11, s3
	v_lshl_add_u64 v[92:93], s[10:11], 2, v[16:17]
	v_pk_mul_f32 v[190:191], v[2:3], v[190:191] op_sel_hi:[1,0]
	s_nop 0
	v_pk_fma_f32 v[190:191], v[12:13], v[18:19], v[190:191]
	global_store_dwordx2 v[92:93], v[190:191], off
	v_mul_f32_e32 v127, v5, v191
	v_fmac_f32_e32 v127, v4, v190
	v_mov_b32_e32 v128, v96
	v_mov_b32_e32 v129, v97
	v_mov_b32_e32 v130, v98
	v_mov_b32_e32 v131, v99
	v_mov_b32_e32 v132, v100
	v_mov_b32_e32 v133, v101
	v_mov_b32_e32 v134, v102
	v_mov_b32_e32 v135, v103
	v_mov_b32_e32 v136, v104
	v_mov_b32_e32 v137, v105
	v_mov_b32_e32 v138, v106
	v_mov_b32_e32 v139, v107
	v_mov_b32_e32 v140, v108
	v_mov_b32_e32 v141, v109
	v_mov_b32_e32 v142, v110
	v_mov_b32_e32 v143, v111
	v_mov_b32_e32 v144, v112
	v_mov_b32_e32 v145, v113
	v_mov_b32_e32 v146, v114
	v_mov_b32_e32 v147, v115
	v_mov_b32_e32 v148, v116
	v_mov_b32_e32 v149, v117
	v_mov_b32_e32 v150, v118
	v_mov_b32_e32 v151, v119
	v_mov_b32_e32 v152, v120
	v_mov_b32_e32 v153, v121
	v_mov_b32_e32 v154, v122
	v_mov_b32_e32 v155, v123
	v_mov_b32_e32 v156, v124
	v_mov_b32_e32 v157, v125
	v_mov_b32_e32 v158, v126
	v_mov_b32_e32 v159, v127
	v_permlane32_swap_b32_e32 v128, v96
	v_permlane32_swap_b32_e32 v129, v97
	v_permlane32_swap_b32_e32 v130, v98
	v_permlane32_swap_b32_e32 v131, v99
	v_permlane32_swap_b32_e32 v132, v100
	v_permlane32_swap_b32_e32 v133, v101
	v_permlane32_swap_b32_e32 v134, v102
	v_permlane32_swap_b32_e32 v135, v103
	v_permlane32_swap_b32_e32 v136, v104
	v_permlane32_swap_b32_e32 v137, v105
	v_permlane32_swap_b32_e32 v138, v106
	v_permlane32_swap_b32_e32 v139, v107
	v_permlane32_swap_b32_e32 v140, v108
	v_permlane32_swap_b32_e32 v141, v109
	v_permlane32_swap_b32_e32 v142, v110
	v_permlane32_swap_b32_e32 v143, v111
	v_permlane32_swap_b32_e32 v144, v112
	v_permlane32_swap_b32_e32 v145, v113
	v_permlane32_swap_b32_e32 v146, v114
	v_permlane32_swap_b32_e32 v147, v115
	v_permlane32_swap_b32_e32 v148, v116
	v_permlane32_swap_b32_e32 v149, v117
	v_permlane32_swap_b32_e32 v150, v118
	v_permlane32_swap_b32_e32 v151, v119
	v_permlane32_swap_b32_e32 v152, v120
	v_permlane32_swap_b32_e32 v153, v121
	v_permlane32_swap_b32_e32 v154, v122
	v_permlane32_swap_b32_e32 v155, v123
	v_permlane32_swap_b32_e32 v156, v124
	v_permlane32_swap_b32_e32 v157, v125
	v_permlane32_swap_b32_e32 v158, v126
	v_permlane32_swap_b32_e32 v159, v127
	v_add_f32_e32 v96, v128, v96
	v_add_f32_e32 v97, v129, v97
	v_add_f32_e32 v98, v130, v98
	v_add_f32_e32 v99, v131, v99
	v_add_f32_e32 v100, v132, v100
	v_add_f32_e32 v101, v133, v101
	v_add_f32_e32 v102, v134, v102
	v_add_f32_e32 v103, v135, v103
	v_add_f32_e32 v104, v136, v104
	v_add_f32_e32 v105, v137, v105
	v_add_f32_e32 v106, v138, v106
	v_add_f32_e32 v107, v139, v107
	v_add_f32_e32 v108, v140, v108
	v_add_f32_e32 v109, v141, v109
	v_add_f32_e32 v110, v142, v110
	v_add_f32_e32 v111, v143, v111
	v_add_f32_e32 v112, v144, v112
	v_add_f32_e32 v113, v145, v113
	v_add_f32_e32 v114, v146, v114
	v_add_f32_e32 v115, v147, v115
	v_add_f32_e32 v116, v148, v116
	v_add_f32_e32 v117, v149, v117
	v_add_f32_e32 v118, v150, v118
	v_add_f32_e32 v119, v151, v119
	v_add_f32_e32 v120, v152, v120
	v_add_f32_e32 v121, v153, v121
	v_add_f32_e32 v122, v154, v122
	v_add_f32_e32 v123, v155, v123
	v_add_f32_e32 v124, v156, v124
	v_add_f32_e32 v125, v157, v125
	v_add_f32_e32 v126, v158, v126
	v_add_f32_e32 v127, v159, v127
	v_mov_b32_e32 v128, v96
	v_mov_b32_e32 v129, v97
	v_mov_b32_e32 v130, v98
	v_mov_b32_e32 v131, v99
	v_mov_b32_e32 v132, v100
	v_mov_b32_e32 v133, v101
	v_mov_b32_e32 v134, v102
	v_mov_b32_e32 v135, v103
	v_mov_b32_e32 v136, v104
	v_mov_b32_e32 v137, v105
	v_mov_b32_e32 v138, v106
	v_mov_b32_e32 v139, v107
	v_mov_b32_e32 v140, v108
	v_mov_b32_e32 v141, v109
	v_mov_b32_e32 v142, v110
	v_mov_b32_e32 v143, v111
	v_mov_b32_e32 v144, v112
	v_mov_b32_e32 v145, v113
	v_mov_b32_e32 v146, v114
	v_mov_b32_e32 v147, v115
	v_mov_b32_e32 v148, v116
	v_mov_b32_e32 v149, v117
	v_mov_b32_e32 v150, v118
	v_mov_b32_e32 v151, v119
	v_mov_b32_e32 v152, v120
	v_mov_b32_e32 v153, v121
	v_mov_b32_e32 v154, v122
	v_mov_b32_e32 v155, v123
	v_mov_b32_e32 v156, v124
	v_mov_b32_e32 v157, v125
	v_mov_b32_e32 v158, v126
	v_mov_b32_e32 v159, v127
	v_permlane16_swap_b32_e32 v128, v96
	v_permlane16_swap_b32_e32 v129, v97
	v_permlane16_swap_b32_e32 v130, v98
	v_permlane16_swap_b32_e32 v131, v99
	v_permlane16_swap_b32_e32 v132, v100
	v_permlane16_swap_b32_e32 v133, v101
	v_permlane16_swap_b32_e32 v134, v102
	v_permlane16_swap_b32_e32 v135, v103
	v_permlane16_swap_b32_e32 v136, v104
	v_permlane16_swap_b32_e32 v137, v105
	v_permlane16_swap_b32_e32 v138, v106
	v_permlane16_swap_b32_e32 v139, v107
	v_permlane16_swap_b32_e32 v140, v108
	v_permlane16_swap_b32_e32 v141, v109
	v_permlane16_swap_b32_e32 v142, v110
	v_permlane16_swap_b32_e32 v143, v111
	v_permlane16_swap_b32_e32 v144, v112
	v_permlane16_swap_b32_e32 v145, v113
	v_permlane16_swap_b32_e32 v146, v114
	v_permlane16_swap_b32_e32 v147, v115
	v_permlane16_swap_b32_e32 v148, v116
	v_permlane16_swap_b32_e32 v149, v117
	v_permlane16_swap_b32_e32 v150, v118
	v_permlane16_swap_b32_e32 v151, v119
	v_permlane16_swap_b32_e32 v152, v120
	v_permlane16_swap_b32_e32 v153, v121
	v_permlane16_swap_b32_e32 v154, v122
	v_permlane16_swap_b32_e32 v155, v123
	v_permlane16_swap_b32_e32 v156, v124
	v_permlane16_swap_b32_e32 v157, v125
	v_permlane16_swap_b32_e32 v158, v126
	v_permlane16_swap_b32_e32 v159, v127
	v_add_f32_e32 v96, v128, v96
	v_add_f32_e32 v97, v129, v97
	v_add_f32_e32 v98, v130, v98
	v_add_f32_e32 v99, v131, v99
	v_add_f32_e32 v100, v132, v100
	v_add_f32_e32 v101, v133, v101
	v_add_f32_e32 v102, v134, v102
	v_add_f32_e32 v103, v135, v103
	v_add_f32_e32 v104, v136, v104
	v_add_f32_e32 v105, v137, v105
	v_add_f32_e32 v106, v138, v106
	v_add_f32_e32 v107, v139, v107
	v_add_f32_e32 v108, v140, v108
	v_add_f32_e32 v109, v141, v109
	v_add_f32_e32 v110, v142, v110
	v_add_f32_e32 v111, v143, v111
	v_add_f32_e32 v112, v144, v112
	v_add_f32_e32 v113, v145, v113
	v_add_f32_e32 v114, v146, v114
	v_add_f32_e32 v115, v147, v115
	v_add_f32_e32 v116, v148, v116
	v_add_f32_e32 v117, v149, v117
	v_add_f32_e32 v118, v150, v118
	v_add_f32_e32 v119, v151, v119
	v_add_f32_e32 v120, v152, v120
	v_add_f32_e32 v121, v153, v121
	v_add_f32_e32 v122, v154, v122
	v_add_f32_e32 v123, v155, v123
	v_add_f32_e32 v124, v156, v124
	v_add_f32_e32 v125, v157, v125
	v_add_f32_e32 v126, v158, v126
	v_add_f32_e32 v127, v159, v127
	v_add_f32_dpp v128, v96, v96 row_ror:8 row_mask:0xf bank_mask:0xf
	v_add_f32_dpp v129, v97, v97 row_ror:8 row_mask:0xf bank_mask:0xf
	v_add_f32_dpp v130, v98, v98 row_ror:8 row_mask:0xf bank_mask:0xf
	v_add_f32_dpp v131, v99, v99 row_ror:8 row_mask:0xf bank_mask:0xf
	v_add_f32_dpp v132, v100, v100 row_ror:8 row_mask:0xf bank_mask:0xf
	v_add_f32_dpp v133, v101, v101 row_ror:8 row_mask:0xf bank_mask:0xf
	v_add_f32_dpp v134, v102, v102 row_ror:8 row_mask:0xf bank_mask:0xf
	v_add_f32_dpp v135, v103, v103 row_ror:8 row_mask:0xf bank_mask:0xf
	v_add_f32_dpp v136, v104, v104 row_ror:8 row_mask:0xf bank_mask:0xf
	v_add_f32_dpp v137, v105, v105 row_ror:8 row_mask:0xf bank_mask:0xf
	v_add_f32_dpp v138, v106, v106 row_ror:8 row_mask:0xf bank_mask:0xf
	v_add_f32_dpp v139, v107, v107 row_ror:8 row_mask:0xf bank_mask:0xf
	v_add_f32_dpp v140, v108, v108 row_ror:8 row_mask:0xf bank_mask:0xf
	v_add_f32_dpp v141, v109, v109 row_ror:8 row_mask:0xf bank_mask:0xf
	v_add_f32_dpp v142, v110, v110 row_ror:8 row_mask:0xf bank_mask:0xf
	v_add_f32_dpp v143, v111, v111 row_ror:8 row_mask:0xf bank_mask:0xf
	v_add_f32_dpp v144, v112, v112 row_ror:8 row_mask:0xf bank_mask:0xf
	v_add_f32_dpp v145, v113, v113 row_ror:8 row_mask:0xf bank_mask:0xf
	v_add_f32_dpp v146, v114, v114 row_ror:8 row_mask:0xf bank_mask:0xf
	v_add_f32_dpp v147, v115, v115 row_ror:8 row_mask:0xf bank_mask:0xf
	v_add_f32_dpp v148, v116, v116 row_ror:8 row_mask:0xf bank_mask:0xf
	v_add_f32_dpp v149, v117, v117 row_ror:8 row_mask:0xf bank_mask:0xf
	v_add_f32_dpp v150, v118, v118 row_ror:8 row_mask:0xf bank_mask:0xf
	v_add_f32_dpp v151, v119, v119 row_ror:8 row_mask:0xf bank_mask:0xf
	v_add_f32_dpp v152, v120, v120 row_ror:8 row_mask:0xf bank_mask:0xf
	v_add_f32_dpp v153, v121, v121 row_ror:8 row_mask:0xf bank_mask:0xf
	v_add_f32_dpp v154, v122, v122 row_ror:8 row_mask:0xf bank_mask:0xf
	v_add_f32_dpp v155, v123, v123 row_ror:8 row_mask:0xf bank_mask:0xf
	v_add_f32_dpp v156, v124, v124 row_ror:8 row_mask:0xf bank_mask:0xf
	v_add_f32_dpp v157, v125, v125 row_ror:8 row_mask:0xf bank_mask:0xf
	v_add_f32_dpp v158, v126, v126 row_ror:8 row_mask:0xf bank_mask:0xf
	v_add_f32_dpp v159, v127, v127 row_ror:8 row_mask:0xf bank_mask:0xf
	v_mov_b32_dpp v96, v128 quad_perm:[3,2,1,0] row_mask:0xf bank_mask:0xf
	v_mov_b32_dpp v97, v129 quad_perm:[3,2,1,0] row_mask:0xf bank_mask:0xf
	v_mov_b32_dpp v98, v130 quad_perm:[3,2,1,0] row_mask:0xf bank_mask:0xf
	v_mov_b32_dpp v99, v131 quad_perm:[3,2,1,0] row_mask:0xf bank_mask:0xf
	v_mov_b32_dpp v100, v132 quad_perm:[3,2,1,0] row_mask:0xf bank_mask:0xf
	v_mov_b32_dpp v101, v133 quad_perm:[3,2,1,0] row_mask:0xf bank_mask:0xf
	v_mov_b32_dpp v102, v134 quad_perm:[3,2,1,0] row_mask:0xf bank_mask:0xf
	v_mov_b32_dpp v103, v135 quad_perm:[3,2,1,0] row_mask:0xf bank_mask:0xf
	v_mov_b32_dpp v104, v136 quad_perm:[3,2,1,0] row_mask:0xf bank_mask:0xf
	v_mov_b32_dpp v105, v137 quad_perm:[3,2,1,0] row_mask:0xf bank_mask:0xf
	v_mov_b32_dpp v106, v138 quad_perm:[3,2,1,0] row_mask:0xf bank_mask:0xf
	v_mov_b32_dpp v107, v139 quad_perm:[3,2,1,0] row_mask:0xf bank_mask:0xf
	v_mov_b32_dpp v108, v140 quad_perm:[3,2,1,0] row_mask:0xf bank_mask:0xf
	v_mov_b32_dpp v109, v141 quad_perm:[3,2,1,0] row_mask:0xf bank_mask:0xf
	v_mov_b32_dpp v110, v142 quad_perm:[3,2,1,0] row_mask:0xf bank_mask:0xf
	v_mov_b32_dpp v111, v143 quad_perm:[3,2,1,0] row_mask:0xf bank_mask:0xf
	v_mov_b32_dpp v112, v144 quad_perm:[3,2,1,0] row_mask:0xf bank_mask:0xf
	v_mov_b32_dpp v113, v145 quad_perm:[3,2,1,0] row_mask:0xf bank_mask:0xf
	v_mov_b32_dpp v114, v146 quad_perm:[3,2,1,0] row_mask:0xf bank_mask:0xf
	v_mov_b32_dpp v115, v147 quad_perm:[3,2,1,0] row_mask:0xf bank_mask:0xf
	v_mov_b32_dpp v116, v148 quad_perm:[3,2,1,0] row_mask:0xf bank_mask:0xf
	v_mov_b32_dpp v117, v149 quad_perm:[3,2,1,0] row_mask:0xf bank_mask:0xf
	v_mov_b32_dpp v118, v150 quad_perm:[3,2,1,0] row_mask:0xf bank_mask:0xf
	v_mov_b32_dpp v119, v151 quad_perm:[3,2,1,0] row_mask:0xf bank_mask:0xf
	v_mov_b32_dpp v120, v152 quad_perm:[3,2,1,0] row_mask:0xf bank_mask:0xf
	v_mov_b32_dpp v121, v153 quad_perm:[3,2,1,0] row_mask:0xf bank_mask:0xf
	v_mov_b32_dpp v122, v154 quad_perm:[3,2,1,0] row_mask:0xf bank_mask:0xf
	v_mov_b32_dpp v123, v155 quad_perm:[3,2,1,0] row_mask:0xf bank_mask:0xf
	v_mov_b32_dpp v124, v156 quad_perm:[3,2,1,0] row_mask:0xf bank_mask:0xf
	v_mov_b32_dpp v125, v157 quad_perm:[3,2,1,0] row_mask:0xf bank_mask:0xf
	v_mov_b32_dpp v126, v158 quad_perm:[3,2,1,0] row_mask:0xf bank_mask:0xf
	v_mov_b32_dpp v127, v159 quad_perm:[3,2,1,0] row_mask:0xf bank_mask:0xf
	v_add_f32_dpp v96, v96, v128 row_half_mirror row_mask:0xf bank_mask:0xf
	v_add_f32_dpp v97, v97, v129 row_half_mirror row_mask:0xf bank_mask:0xf
	v_add_f32_dpp v98, v98, v130 row_half_mirror row_mask:0xf bank_mask:0xf
	v_add_f32_dpp v99, v99, v131 row_half_mirror row_mask:0xf bank_mask:0xf
	v_add_f32_dpp v100, v100, v132 row_half_mirror row_mask:0xf bank_mask:0xf
	v_add_f32_dpp v101, v101, v133 row_half_mirror row_mask:0xf bank_mask:0xf
	v_add_f32_dpp v102, v102, v134 row_half_mirror row_mask:0xf bank_mask:0xf
	v_add_f32_dpp v103, v103, v135 row_half_mirror row_mask:0xf bank_mask:0xf
	v_add_f32_dpp v104, v104, v136 row_half_mirror row_mask:0xf bank_mask:0xf
	v_add_f32_dpp v105, v105, v137 row_half_mirror row_mask:0xf bank_mask:0xf
	v_add_f32_dpp v106, v106, v138 row_half_mirror row_mask:0xf bank_mask:0xf
	v_add_f32_dpp v107, v107, v139 row_half_mirror row_mask:0xf bank_mask:0xf
	v_add_f32_dpp v108, v108, v140 row_half_mirror row_mask:0xf bank_mask:0xf
	v_add_f32_dpp v109, v109, v141 row_half_mirror row_mask:0xf bank_mask:0xf
	v_add_f32_dpp v110, v110, v142 row_half_mirror row_mask:0xf bank_mask:0xf
	v_add_f32_dpp v111, v111, v143 row_half_mirror row_mask:0xf bank_mask:0xf
	v_add_f32_dpp v112, v112, v144 row_half_mirror row_mask:0xf bank_mask:0xf
	v_add_f32_dpp v113, v113, v145 row_half_mirror row_mask:0xf bank_mask:0xf
	v_add_f32_dpp v114, v114, v146 row_half_mirror row_mask:0xf bank_mask:0xf
	v_add_f32_dpp v115, v115, v147 row_half_mirror row_mask:0xf bank_mask:0xf
	v_add_f32_dpp v116, v116, v148 row_half_mirror row_mask:0xf bank_mask:0xf
	v_add_f32_dpp v117, v117, v149 row_half_mirror row_mask:0xf bank_mask:0xf
	v_add_f32_dpp v118, v118, v150 row_half_mirror row_mask:0xf bank_mask:0xf
	v_add_f32_dpp v119, v119, v151 row_half_mirror row_mask:0xf bank_mask:0xf
	v_add_f32_dpp v120, v120, v152 row_half_mirror row_mask:0xf bank_mask:0xf
	v_add_f32_dpp v121, v121, v153 row_half_mirror row_mask:0xf bank_mask:0xf
	v_add_f32_dpp v122, v122, v154 row_half_mirror row_mask:0xf bank_mask:0xf
	v_add_f32_dpp v123, v123, v155 row_half_mirror row_mask:0xf bank_mask:0xf
	v_add_f32_dpp v124, v124, v156 row_half_mirror row_mask:0xf bank_mask:0xf
	v_add_f32_dpp v125, v125, v157 row_half_mirror row_mask:0xf bank_mask:0xf
	v_add_f32_dpp v126, v126, v158 row_half_mirror row_mask:0xf bank_mask:0xf
	v_add_f32_dpp v127, v127, v159 row_half_mirror row_mask:0xf bank_mask:0xf
	v_add_f32_dpp v128, v96, v96 quad_perm:[2,3,0,1] row_mask:0xf bank_mask:0xf
	v_add_f32_dpp v129, v97, v97 quad_perm:[2,3,0,1] row_mask:0xf bank_mask:0xf
	v_add_f32_dpp v130, v98, v98 quad_perm:[2,3,0,1] row_mask:0xf bank_mask:0xf
	v_add_f32_dpp v131, v99, v99 quad_perm:[2,3,0,1] row_mask:0xf bank_mask:0xf
	v_add_f32_dpp v132, v100, v100 quad_perm:[2,3,0,1] row_mask:0xf bank_mask:0xf
	v_add_f32_dpp v133, v101, v101 quad_perm:[2,3,0,1] row_mask:0xf bank_mask:0xf
	v_add_f32_dpp v134, v102, v102 quad_perm:[2,3,0,1] row_mask:0xf bank_mask:0xf
	v_add_f32_dpp v135, v103, v103 quad_perm:[2,3,0,1] row_mask:0xf bank_mask:0xf
	v_add_f32_dpp v136, v104, v104 quad_perm:[2,3,0,1] row_mask:0xf bank_mask:0xf
	v_add_f32_dpp v137, v105, v105 quad_perm:[2,3,0,1] row_mask:0xf bank_mask:0xf
	v_add_f32_dpp v138, v106, v106 quad_perm:[2,3,0,1] row_mask:0xf bank_mask:0xf
	v_add_f32_dpp v139, v107, v107 quad_perm:[2,3,0,1] row_mask:0xf bank_mask:0xf
	v_add_f32_dpp v140, v108, v108 quad_perm:[2,3,0,1] row_mask:0xf bank_mask:0xf
	v_add_f32_dpp v141, v109, v109 quad_perm:[2,3,0,1] row_mask:0xf bank_mask:0xf
	v_add_f32_dpp v142, v110, v110 quad_perm:[2,3,0,1] row_mask:0xf bank_mask:0xf
	v_add_f32_dpp v143, v111, v111 quad_perm:[2,3,0,1] row_mask:0xf bank_mask:0xf
	v_add_f32_dpp v144, v112, v112 quad_perm:[2,3,0,1] row_mask:0xf bank_mask:0xf
	v_add_f32_dpp v145, v113, v113 quad_perm:[2,3,0,1] row_mask:0xf bank_mask:0xf
	v_add_f32_dpp v146, v114, v114 quad_perm:[2,3,0,1] row_mask:0xf bank_mask:0xf
	v_add_f32_dpp v147, v115, v115 quad_perm:[2,3,0,1] row_mask:0xf bank_mask:0xf
	v_add_f32_dpp v148, v116, v116 quad_perm:[2,3,0,1] row_mask:0xf bank_mask:0xf
	v_add_f32_dpp v149, v117, v117 quad_perm:[2,3,0,1] row_mask:0xf bank_mask:0xf
	v_add_f32_dpp v150, v118, v118 quad_perm:[2,3,0,1] row_mask:0xf bank_mask:0xf
	v_add_f32_dpp v151, v119, v119 quad_perm:[2,3,0,1] row_mask:0xf bank_mask:0xf
	v_add_f32_dpp v152, v120, v120 quad_perm:[2,3,0,1] row_mask:0xf bank_mask:0xf
	v_add_f32_dpp v153, v121, v121 quad_perm:[2,3,0,1] row_mask:0xf bank_mask:0xf
	v_add_f32_dpp v154, v122, v122 quad_perm:[2,3,0,1] row_mask:0xf bank_mask:0xf
	v_add_f32_dpp v155, v123, v123 quad_perm:[2,3,0,1] row_mask:0xf bank_mask:0xf
	v_add_f32_dpp v156, v124, v124 quad_perm:[2,3,0,1] row_mask:0xf bank_mask:0xf
	v_add_f32_dpp v157, v125, v125 quad_perm:[2,3,0,1] row_mask:0xf bank_mask:0xf
	v_add_f32_dpp v158, v126, v126 quad_perm:[2,3,0,1] row_mask:0xf bank_mask:0xf
	v_add_f32_dpp v159, v127, v127 quad_perm:[2,3,0,1] row_mask:0xf bank_mask:0xf
	v_add_f32_dpp v96, v128, v128 quad_perm:[1,0,3,2] row_mask:0xf bank_mask:0xf
	v_add_f32_dpp v97, v129, v129 quad_perm:[1,0,3,2] row_mask:0xf bank_mask:0xf
	v_add_f32_dpp v98, v130, v130 quad_perm:[1,0,3,2] row_mask:0xf bank_mask:0xf
	v_add_f32_dpp v99, v131, v131 quad_perm:[1,0,3,2] row_mask:0xf bank_mask:0xf
	v_add_f32_dpp v100, v132, v132 quad_perm:[1,0,3,2] row_mask:0xf bank_mask:0xf
	v_add_f32_dpp v101, v133, v133 quad_perm:[1,0,3,2] row_mask:0xf bank_mask:0xf
	v_add_f32_dpp v102, v134, v134 quad_perm:[1,0,3,2] row_mask:0xf bank_mask:0xf
	v_add_f32_dpp v103, v135, v135 quad_perm:[1,0,3,2] row_mask:0xf bank_mask:0xf
	v_add_f32_dpp v104, v136, v136 quad_perm:[1,0,3,2] row_mask:0xf bank_mask:0xf
	v_add_f32_dpp v105, v137, v137 quad_perm:[1,0,3,2] row_mask:0xf bank_mask:0xf
	v_add_f32_dpp v106, v138, v138 quad_perm:[1,0,3,2] row_mask:0xf bank_mask:0xf
	v_add_f32_dpp v107, v139, v139 quad_perm:[1,0,3,2] row_mask:0xf bank_mask:0xf
	v_add_f32_dpp v108, v140, v140 quad_perm:[1,0,3,2] row_mask:0xf bank_mask:0xf
	v_add_f32_dpp v109, v141, v141 quad_perm:[1,0,3,2] row_mask:0xf bank_mask:0xf
	v_add_f32_dpp v110, v142, v142 quad_perm:[1,0,3,2] row_mask:0xf bank_mask:0xf
	v_add_f32_dpp v111, v143, v143 quad_perm:[1,0,3,2] row_mask:0xf bank_mask:0xf
	v_add_f32_dpp v112, v144, v144 quad_perm:[1,0,3,2] row_mask:0xf bank_mask:0xf
	v_add_f32_dpp v113, v145, v145 quad_perm:[1,0,3,2] row_mask:0xf bank_mask:0xf
	v_add_f32_dpp v114, v146, v146 quad_perm:[1,0,3,2] row_mask:0xf bank_mask:0xf
	v_add_f32_dpp v115, v147, v147 quad_perm:[1,0,3,2] row_mask:0xf bank_mask:0xf
	v_add_f32_dpp v116, v148, v148 quad_perm:[1,0,3,2] row_mask:0xf bank_mask:0xf
	v_add_f32_dpp v117, v149, v149 quad_perm:[1,0,3,2] row_mask:0xf bank_mask:0xf
	v_add_f32_dpp v118, v150, v150 quad_perm:[1,0,3,2] row_mask:0xf bank_mask:0xf
	v_add_f32_dpp v119, v151, v151 quad_perm:[1,0,3,2] row_mask:0xf bank_mask:0xf
	v_add_f32_dpp v120, v152, v152 quad_perm:[1,0,3,2] row_mask:0xf bank_mask:0xf
	v_add_f32_dpp v121, v153, v153 quad_perm:[1,0,3,2] row_mask:0xf bank_mask:0xf
	v_add_f32_dpp v122, v154, v154 quad_perm:[1,0,3,2] row_mask:0xf bank_mask:0xf
	v_add_f32_dpp v123, v155, v155 quad_perm:[1,0,3,2] row_mask:0xf bank_mask:0xf
	v_add_f32_dpp v124, v156, v156 quad_perm:[1,0,3,2] row_mask:0xf bank_mask:0xf
	v_add_f32_dpp v125, v157, v157 quad_perm:[1,0,3,2] row_mask:0xf bank_mask:0xf
	v_add_f32_dpp v126, v158, v158 quad_perm:[1,0,3,2] row_mask:0xf bank_mask:0xf
	v_add_f32_dpp v127, v159, v159 quad_perm:[1,0,3,2] row_mask:0xf bank_mask:0xf
	s_and_saveexec_b64 s[10:11], s[4:5]
	ds_write_b32 v87, v96 offset:6144
	ds_write_b32 v87, v97 offset:6148
	ds_write_b32 v87, v98 offset:6152
	ds_write_b32 v87, v99 offset:6156
	ds_write_b32 v87, v100 offset:6160
	ds_write_b32 v87, v101 offset:6164
	ds_write_b32 v87, v102 offset:6168
	ds_write_b32 v87, v103 offset:6172
	ds_write_b32 v87, v104 offset:6176
	ds_write_b32 v87, v105 offset:6180
	ds_write_b32 v87, v106 offset:6184
	ds_write_b32 v87, v107 offset:6188
	ds_write_b32 v87, v108 offset:6192
	ds_write_b32 v87, v109 offset:6196
	ds_write_b32 v87, v110 offset:6200
	ds_write_b32 v87, v111 offset:6204
	ds_write_b32 v87, v112 offset:6208
	ds_write_b32 v87, v113 offset:6212
	ds_write_b32 v87, v114 offset:6216
	ds_write_b32 v87, v115 offset:6220
	ds_write_b32 v87, v116 offset:6224
	ds_write_b32 v87, v117 offset:6228
	ds_write_b32 v87, v118 offset:6232
	ds_write_b32 v87, v119 offset:6236
	ds_write_b32 v87, v120 offset:6240
	ds_write_b32 v87, v121 offset:6244
	ds_write_b32 v87, v122 offset:6248
	ds_write_b32 v87, v123 offset:6252
	ds_write_b32 v87, v124 offset:6256
	ds_write_b32 v87, v125 offset:6260
	ds_write_b32 v87, v126 offset:6264
	ds_write_b32 v87, v127 offset:6268
	s_branch .LBB0_333
	s_nop 0
	s_nop 0
	s_nop 0
	s_nop 0
	s_nop 0
	s_nop 0
	s_nop 0
	s_nop 0
	s_nop 0
	s_nop 0
	s_nop 0
	s_nop 0
	s_nop 0
